# v122 stack plus relaxed waits 1-3 of the first K trip after an epilogue (in-proj both copies, ffn-up): only wait 4 depends on loads younger than the epilogue stores
# speedup vs baseline: 1.0011x; 1.0011x over previous
.Lrwd_fu1:
	s_waitcnt lgkmcnt(0)
	s_barrier
	s_setprio 1
	s_waitcnt lgkmcnt(0)
	v_mfma_f32_16x16x32_bf16 v[60:63], v[144:147], v[178:181], v[60:63]
	v_mfma_f32_16x16x32_bf16 v[52:55], v[152:155], v[178:181], v[52:55]
	v_mfma_f32_16x16x32_bf16 v[44:47], v[144:147], v[186:189], v[44:47]
	v_mfma_f32_16x16x32_bf16 v[36:39], v[152:155], v[186:189], v[36:39]
	v_mfma_f32_16x16x32_bf16 v[28:31], v[144:147], v[212:215], v[28:31]
	v_mfma_f32_16x16x32_bf16 v[20:23], v[152:155], v[212:215], v[20:23]
	v_mfma_f32_16x16x32_bf16 v[12:15], v[144:147], v[220:223], v[12:15]
	v_mfma_f32_16x16x32_bf16 v[4:7], v[152:155], v[220:223], v[4:7]
	v_mfma_f32_16x16x32_bf16 v[60:63], v[148:151], v[182:185], v[60:63]
	v_mfma_f32_16x16x32_bf16 v[52:55], v[156:159], v[182:185], v[52:55]
	v_mfma_f32_16x16x32_bf16 v[44:47], v[148:151], v[208:211], v[44:47]
	v_mfma_f32_16x16x32_bf16 v[36:39], v[156:159], v[208:211], v[36:39]
	v_mfma_f32_16x16x32_bf16 v[28:31], v[148:151], v[216:219], v[28:31]
	v_mfma_f32_16x16x32_bf16 v[20:23], v[156:159], v[216:219], v[20:23]
	v_mfma_f32_16x16x32_bf16 v[12:15], v[148:151], v[224:227], v[12:15]
	v_mfma_f32_16x16x32_bf16 v[4:7], v[156:159], v[224:227], v[4:7]
	s_setprio 0
	s_setprio 1
	v_mfma_f32_16x16x32_bf16 v[56:59], v[160:163], v[178:181], v[56:59]
	v_mfma_f32_16x16x32_bf16 v[48:51], v[168:171], v[178:181], v[48:51]
	v_mfma_f32_16x16x32_bf16 v[40:43], v[160:163], v[186:189], v[40:43]
	v_mfma_f32_16x16x32_bf16 v[32:35], v[168:171], v[186:189], v[32:35]
	v_mfma_f32_16x16x32_bf16 v[24:27], v[160:163], v[212:215], v[24:27]
	v_mfma_f32_16x16x32_bf16 v[16:19], v[168:171], v[212:215], v[16:19]
	v_mfma_f32_16x16x32_bf16 v[8:11], v[160:163], v[220:223], v[8:11]
	v_mfma_f32_16x16x32_bf16 v[0:3], v[168:171], v[220:223], v[0:3]
	v_mfma_f32_16x16x32_bf16 v[56:59], v[164:167], v[182:185], v[56:59]
	v_mfma_f32_16x16x32_bf16 v[48:51], v[172:175], v[182:185], v[48:51]
	v_mfma_f32_16x16x32_bf16 v[40:43], v[164:167], v[208:211], v[40:43]
	v_mfma_f32_16x16x32_bf16 v[32:35], v[172:175], v[208:211], v[32:35]
	v_mfma_f32_16x16x32_bf16 v[24:27], v[164:167], v[216:219], v[24:27]
	v_mfma_f32_16x16x32_bf16 v[16:19], v[172:175], v[216:219], v[16:19]
	v_mfma_f32_16x16x32_bf16 v[8:11], v[164:167], v[224:227], v[8:11]
	v_mfma_f32_16x16x32_bf16 v[0:3], v[172:175], v[224:227], v[0:3]
	s_setprio 0
	s_barrier
	s_add_i32 s22, 0, 0x18000
	s_add_i32 s37, 0, 0x1c000
	v_add_u32_e32 v156, s22, v142
	v_add_u32_e32 v172, s37, v142
	ds_read_b128 v[144:147], v156
	ds_read_b128 v[148:151], v156 offset:1024
	ds_read_b128 v[152:155], v156 offset:2048
	ds_read_b128 v[156:159], v156 offset:3072
	ds_read_b128 v[160:163], v172
	ds_read_b128 v[164:167], v172 offset:1024
	ds_read_b128 v[168:171], v172 offset:2048
	ds_read_b128 v[172:175], v172 offset:3072
	s_add_u32 s0, s60, 0x40000
	s_addc_u32 s1, s61, 0
	s_mov_b32 m0, s68
	v_lshl_add_u64 v[236:237], s[0:1], 0, v[134:135]
	ds_read_b128 v[178:181], v143 offset:32768
	ds_read_b128 v[182:185], v143 offset:33792
	ds_read_b128 v[186:189], v143 offset:34816
	ds_read_b128 v[208:211], v143 offset:35840
	ds_read_b128 v[212:215], v143 offset:36864
	ds_read_b128 v[216:219], v143 offset:37888
	ds_read_b128 v[220:223], v143 offset:38912
	ds_read_b128 v[224:227], v143 offset:39936
	global_load_lds_dwordx4 v[236:237], off
	v_lshl_add_u64 v[236:237], s[0:1], 0, v[130:131]
	s_mov_b32 m0, s69
	s_nop 0
	global_load_lds_dwordx4 v[236:237], off
	s_cmp_eq_u32 s64, -2
	s_cbranch_scc0 .Lrw8_fu2
	s_cmp_gt_u32 s50, 1
	s_cbranch_scc0 .Lrw8_fu2
	s_waitcnt vmcnt(18)
	s_branch .Lrwd_fu2

.Lrwd_fu2:
	s_waitcnt lgkmcnt(0)
	s_barrier
	s_setprio 1
	s_waitcnt lgkmcnt(0)
	v_mfma_f32_16x16x32_bf16 v[124:127], v[144:147], v[178:181], v[124:127]
	v_mfma_f32_16x16x32_bf16 v[116:119], v[152:155], v[178:181], v[116:119]
	v_mfma_f32_16x16x32_bf16 v[108:111], v[144:147], v[186:189], v[108:111]
	v_mfma_f32_16x16x32_bf16 v[100:103], v[152:155], v[186:189], v[100:103]
	v_mfma_f32_16x16x32_bf16 v[92:95], v[144:147], v[212:215], v[92:95]
	v_mfma_f32_16x16x32_bf16 v[84:87], v[152:155], v[212:215], v[84:87]
	v_mfma_f32_16x16x32_bf16 v[76:79], v[144:147], v[220:223], v[76:79]
	v_mfma_f32_16x16x32_bf16 v[68:71], v[152:155], v[220:223], v[68:71]
	v_mfma_f32_16x16x32_bf16 v[124:127], v[148:151], v[182:185], v[124:127]
	v_mfma_f32_16x16x32_bf16 v[116:119], v[156:159], v[182:185], v[116:119]
	v_mfma_f32_16x16x32_bf16 v[108:111], v[148:151], v[208:211], v[108:111]
	v_mfma_f32_16x16x32_bf16 v[100:103], v[156:159], v[208:211], v[100:103]
	v_mfma_f32_16x16x32_bf16 v[92:95], v[148:151], v[216:219], v[92:95]
	v_mfma_f32_16x16x32_bf16 v[84:87], v[156:159], v[216:219], v[84:87]
	v_mfma_f32_16x16x32_bf16 v[76:79], v[148:151], v[224:227], v[76:79]
	v_mfma_f32_16x16x32_bf16 v[68:71], v[156:159], v[224:227], v[68:71]
	s_setprio 0
	s_setprio 1
	v_mfma_f32_16x16x32_bf16 v[120:123], v[160:163], v[178:181], v[120:123]
	v_mfma_f32_16x16x32_bf16 v[112:115], v[168:171], v[178:181], v[112:115]
	v_mfma_f32_16x16x32_bf16 v[104:107], v[160:163], v[186:189], v[104:107]
	v_mfma_f32_16x16x32_bf16 v[96:99], v[168:171], v[186:189], v[96:99]
	v_mfma_f32_16x16x32_bf16 v[88:91], v[160:163], v[212:215], v[88:91]
	v_mfma_f32_16x16x32_bf16 v[80:83], v[168:171], v[212:215], v[80:83]
	v_mfma_f32_16x16x32_bf16 v[72:75], v[160:163], v[220:223], v[72:75]
	v_mfma_f32_16x16x32_bf16 v[64:67], v[168:171], v[220:223], v[64:67]
	v_mfma_f32_16x16x32_bf16 v[120:123], v[164:167], v[182:185], v[120:123]
	v_mfma_f32_16x16x32_bf16 v[112:115], v[172:175], v[182:185], v[112:115]
	v_mfma_f32_16x16x32_bf16 v[104:107], v[164:167], v[208:211], v[104:107]
	v_mfma_f32_16x16x32_bf16 v[96:99], v[172:175], v[208:211], v[96:99]
	v_mfma_f32_16x16x32_bf16 v[88:91], v[164:167], v[216:219], v[88:91]
	v_mfma_f32_16x16x32_bf16 v[80:83], v[172:175], v[216:219], v[80:83]
	v_mfma_f32_16x16x32_bf16 v[72:75], v[164:167], v[224:227], v[72:75]
	v_mfma_f32_16x16x32_bf16 v[64:67], v[172:175], v[224:227], v[64:67]
	s_setprio 0
	s_barrier
	s_add_i32 s0, s22, s35
	v_lshl_add_u64 v[228:229], v[228:229], 0, s[26:27]
	s_mov_b32 m0, s0
	ds_read_b128 v[178:181], v143 offset:49152
	ds_read_b128 v[182:185], v143 offset:50176
	ds_read_b128 v[186:189], v143 offset:51200
	ds_read_b128 v[208:211], v143 offset:52224
	ds_read_b128 v[212:215], v143 offset:53248
	ds_read_b128 v[216:219], v143 offset:54272
	ds_read_b128 v[220:223], v143 offset:55296
	ds_read_b128 v[224:227], v143 offset:56320
	global_load_lds_dwordx4 v[228:229], off
	s_add_i32 m0, s0, 0x2000
	s_add_u32 s0, s58, 0x10080
	v_lshl_add_u64 v[228:229], v[230:231], 0, s[26:27]
	s_addc_u32 s1, s59, 0
	s_add_i32 s22, s37, s35
	global_load_lds_dwordx4 v[228:229], off
	v_lshl_add_u64 v[228:229], s[0:1], 0, v[132:133]
	s_mov_b32 m0, s22
	s_nop 0
	global_load_lds_dwordx4 v[228:229], off
	v_lshl_add_u64 v[228:229], s[0:1], 0, v[128:129]
	s_add_i32 m0, s22, 0x2000
	s_nop 0
	global_load_lds_dwordx4 v[228:229], off
	v_lshl_add_u64 v[228:229], v[232:233], 0, s[26:27]
	s_mov_b32 m0, s48
	s_nop 0
	global_load_lds_dwordx4 v[228:229], off
	v_lshl_add_u64 v[228:229], v[234:235], 0, s[26:27]
	s_mov_b32 m0, s49
	s_nop 0
	global_load_lds_dwordx4 v[228:229], off
	s_waitcnt vmcnt(8)
	s_waitcnt lgkmcnt(0)
	s_barrier
	s_setprio 1
	s_waitcnt lgkmcnt(0)
	v_mfma_f32_16x16x32_bf16 v[60:63], v[144:147], v[178:181], v[60:63]
	v_mfma_f32_16x16x32_bf16 v[52:55], v[152:155], v[178:181], v[52:55]
	v_mfma_f32_16x16x32_bf16 v[44:47], v[144:147], v[186:189], v[44:47]
	v_mfma_f32_16x16x32_bf16 v[36:39], v[152:155], v[186:189], v[36:39]
	v_mfma_f32_16x16x32_bf16 v[28:31], v[144:147], v[212:215], v[28:31]
	v_mfma_f32_16x16x32_bf16 v[20:23], v[152:155], v[212:215], v[20:23]
	v_mfma_f32_16x16x32_bf16 v[12:15], v[144:147], v[220:223], v[12:15]
	v_mfma_f32_16x16x32_bf16 v[4:7], v[152:155], v[220:223], v[4:7]
	v_mfma_f32_16x16x32_bf16 v[60:63], v[148:151], v[182:185], v[60:63]
	v_mfma_f32_16x16x32_bf16 v[52:55], v[156:159], v[182:185], v[52:55]
	v_mfma_f32_16x16x32_bf16 v[44:47], v[148:151], v[208:211], v[44:47]
	v_mfma_f32_16x16x32_bf16 v[36:39], v[156:159], v[208:211], v[36:39]
	v_mfma_f32_16x16x32_bf16 v[28:31], v[148:151], v[216:219], v[28:31]
	v_mfma_f32_16x16x32_bf16 v[20:23], v[156:159], v[216:219], v[20:23]
	v_mfma_f32_16x16x32_bf16 v[12:15], v[148:151], v[224:227], v[12:15]
	v_mfma_f32_16x16x32_bf16 v[4:7], v[156:159], v[224:227], v[4:7]
	s_setprio 0
	s_setprio 1
	v_mfma_f32_16x16x32_bf16 v[56:59], v[160:163], v[178:181], v[56:59]
	v_mfma_f32_16x16x32_bf16 v[48:51], v[168:171], v[178:181], v[48:51]
	v_mfma_f32_16x16x32_bf16 v[40:43], v[160:163], v[186:189], v[40:43]
	v_mfma_f32_16x16x32_bf16 v[32:35], v[168:171], v[186:189], v[32:35]
	v_mfma_f32_16x16x32_bf16 v[24:27], v[160:163], v[212:215], v[24:27]
	v_mfma_f32_16x16x32_bf16 v[16:19], v[168:171], v[212:215], v[16:19]
	v_mfma_f32_16x16x32_bf16 v[8:11], v[160:163], v[220:223], v[8:11]
	v_mfma_f32_16x16x32_bf16 v[0:3], v[168:171], v[220:223], v[0:3]
	v_mfma_f32_16x16x32_bf16 v[56:59], v[164:167], v[182:185], v[56:59]
	v_mfma_f32_16x16x32_bf16 v[48:51], v[172:175], v[182:185], v[48:51]
	v_mfma_f32_16x16x32_bf16 v[40:43], v[164:167], v[208:211], v[40:43]
	v_mfma_f32_16x16x32_bf16 v[32:35], v[172:175], v[208:211], v[32:35]
	v_mfma_f32_16x16x32_bf16 v[24:27], v[164:167], v[216:219], v[24:27]
	v_mfma_f32_16x16x32_bf16 v[16:19], v[172:175], v[216:219], v[16:19]
	v_mfma_f32_16x16x32_bf16 v[8:11], v[164:167], v[224:227], v[8:11]
	v_mfma_f32_16x16x32_bf16 v[0:3], v[172:175], v[224:227], v[0:3]
	s_setprio 0
	s_barrier
	s_add_i32 s64, s64, 2
	s_add_u32 s56, s56, 0x100
	s_addc_u32 s57, s57, 0
	s_add_u32 s62, s62, 0x100
	s_addc_u32 s63, s63, 0
	s_cmp_gt_u32 s64, 13
	s_cbranch_scc0 .LBB0_58
	v_readlane_b32 s0, v252, 28
	v_readlane_b32 s1, v252, 29
	s_and_b64 vcc, exec, s[0:1]
	s_cbranch_vccz .LBB0_61
	s_barrier

.Lrwd_ip1:
	s_waitcnt lgkmcnt(0)
	s_barrier
	s_setprio 1
	s_waitcnt lgkmcnt(0)
	v_mfma_f32_16x16x32_bf16 v[60:63], v[146:149], v[212:215], v[60:63]
	v_mfma_f32_16x16x32_bf16 v[56:59], v[154:157], v[212:215], v[56:59]
	v_mfma_f32_16x16x32_bf16 v[52:55], v[146:149], v[220:223], v[52:55]
	v_mfma_f32_16x16x32_bf16 v[48:51], v[154:157], v[220:223], v[48:51]
	v_mfma_f32_16x16x32_bf16 v[36:39], v[146:149], v[228:231], v[36:39]
	v_mfma_f32_16x16x32_bf16 v[32:35], v[154:157], v[228:231], v[32:35]
	v_mfma_f32_16x16x32_bf16 v[20:23], v[146:149], v[236:239], v[20:23]
	v_mfma_f32_16x16x32_bf16 v[16:19], v[154:157], v[236:239], v[16:19]
	v_mfma_f32_16x16x32_bf16 v[60:63], v[150:153], v[216:219], v[60:63]
	v_mfma_f32_16x16x32_bf16 v[56:59], v[170:173], v[216:219], v[56:59]
	v_mfma_f32_16x16x32_bf16 v[52:55], v[150:153], v[224:227], v[52:55]
	v_mfma_f32_16x16x32_bf16 v[48:51], v[170:173], v[224:227], v[48:51]
	v_mfma_f32_16x16x32_bf16 v[36:39], v[150:153], v[232:235], v[36:39]
	v_mfma_f32_16x16x32_bf16 v[32:35], v[170:173], v[232:235], v[32:35]
	v_mfma_f32_16x16x32_bf16 v[20:23], v[150:153], v[240:243], v[20:23]
	v_mfma_f32_16x16x32_bf16 v[16:19], v[170:173], v[240:243], v[16:19]
	s_setprio 0
	s_setprio 1
	v_mfma_f32_16x16x32_bf16 v[44:47], v[178:181], v[212:215], v[44:47]
	v_mfma_f32_16x16x32_bf16 v[40:43], v[186:189], v[212:215], v[40:43]
	v_mfma_f32_16x16x32_bf16 v[28:31], v[178:181], v[220:223], v[28:31]
	v_mfma_f32_16x16x32_bf16 v[24:27], v[186:189], v[220:223], v[24:27]
	v_mfma_f32_16x16x32_bf16 v[12:15], v[178:181], v[228:231], v[12:15]
	v_mfma_f32_16x16x32_bf16 v[8:11], v[186:189], v[228:231], v[8:11]
	v_mfma_f32_16x16x32_bf16 v[4:7], v[178:181], v[236:239], v[4:7]
	v_mfma_f32_16x16x32_bf16 v[0:3], v[186:189], v[236:239], v[0:3]
	v_mfma_f32_16x16x32_bf16 v[44:47], v[182:185], v[216:219], v[44:47]
	v_mfma_f32_16x16x32_bf16 v[40:43], v[208:211], v[216:219], v[40:43]
	v_mfma_f32_16x16x32_bf16 v[28:31], v[182:185], v[224:227], v[28:31]
	v_mfma_f32_16x16x32_bf16 v[24:27], v[208:211], v[224:227], v[24:27]
	v_mfma_f32_16x16x32_bf16 v[12:15], v[182:185], v[232:235], v[12:15]
	v_mfma_f32_16x16x32_bf16 v[8:11], v[208:211], v[232:235], v[8:11]
	v_mfma_f32_16x16x32_bf16 v[4:7], v[182:185], v[240:243], v[4:7]
	v_mfma_f32_16x16x32_bf16 v[0:3], v[208:211], v[240:243], v[0:3]
	s_setprio 0
	s_barrier
	s_add_i32 s37, 0, 0x18000
	v_add_u32_e32 v145, s37, v162
	s_add_i32 s39, 0, 0x1c000
	ds_read_b128 v[146:149], v145
	ds_read_b128 v[150:153], v145 offset:1024
	ds_read_b128 v[154:157], v145 offset:2048
	ds_read_b128 v[170:173], v145 offset:3072
	v_add_u32_e32 v145, s39, v162
	ds_read_b128 v[178:181], v145
	ds_read_b128 v[182:185], v145 offset:1024
	ds_read_b128 v[186:189], v145 offset:2048
	ds_read_b128 v[208:211], v145 offset:3072
	s_add_u32 s62, s62, 0x40000
	s_addc_u32 s63, s63, 0
	s_mov_b32 m0, s54
	v_lshl_add_u64 v[248:249], s[62:63], 0, v[134:135]
	ds_read_b128 v[212:215], v168 offset:32768
	ds_read_b128 v[216:219], v168 offset:33792
	ds_read_b128 v[220:223], v168 offset:34816
	ds_read_b128 v[224:227], v168 offset:35840
	ds_read_b128 v[228:231], v168 offset:36864
	ds_read_b128 v[232:235], v168 offset:37888
	ds_read_b128 v[236:239], v168 offset:38912
	ds_read_b128 v[240:243], v168 offset:39936
	global_load_lds_dwordx4 v[248:249], off
	v_lshl_add_u64 v[248:249], s[62:63], 0, v[130:131]
	s_mov_b32 m0, s55
	s_nop 0
	global_load_lds_dwordx4 v[248:249], off
	s_cmp_eq_u32 s64, -2
	s_cbranch_scc0 .Lrw8_ip2
	s_cmp_gt_u32 s35, 1
	s_cbranch_scc0 .Lrw8_ip2
	s_waitcnt vmcnt(26)
	s_branch .Lrwd_ip2

.Lrwd_ip2:
	s_waitcnt lgkmcnt(0)
	s_barrier
	s_setprio 1
	s_waitcnt lgkmcnt(0)
	v_mfma_f32_16x16x32_bf16 v[124:127], v[146:149], v[212:215], v[124:127]
	v_mfma_f32_16x16x32_bf16 v[120:123], v[154:157], v[212:215], v[120:123]
	v_mfma_f32_16x16x32_bf16 v[116:119], v[146:149], v[220:223], v[116:119]
	v_mfma_f32_16x16x32_bf16 v[112:115], v[154:157], v[220:223], v[112:115]
	v_mfma_f32_16x16x32_bf16 v[100:103], v[146:149], v[228:231], v[100:103]
	v_mfma_f32_16x16x32_bf16 v[96:99], v[154:157], v[228:231], v[96:99]
	v_mfma_f32_16x16x32_bf16 v[84:87], v[146:149], v[236:239], v[84:87]
	v_mfma_f32_16x16x32_bf16 v[80:83], v[154:157], v[236:239], v[80:83]
	v_mfma_f32_16x16x32_bf16 v[124:127], v[150:153], v[216:219], v[124:127]
	v_mfma_f32_16x16x32_bf16 v[120:123], v[170:173], v[216:219], v[120:123]
	v_mfma_f32_16x16x32_bf16 v[116:119], v[150:153], v[224:227], v[116:119]
	v_mfma_f32_16x16x32_bf16 v[112:115], v[170:173], v[224:227], v[112:115]
	v_mfma_f32_16x16x32_bf16 v[100:103], v[150:153], v[232:235], v[100:103]
	v_mfma_f32_16x16x32_bf16 v[96:99], v[170:173], v[232:235], v[96:99]
	v_mfma_f32_16x16x32_bf16 v[84:87], v[150:153], v[240:243], v[84:87]
	v_mfma_f32_16x16x32_bf16 v[80:83], v[170:173], v[240:243], v[80:83]
	s_setprio 0
	s_setprio 1
	v_mfma_f32_16x16x32_bf16 v[108:111], v[178:181], v[212:215], v[108:111]
	v_mfma_f32_16x16x32_bf16 v[104:107], v[186:189], v[212:215], v[104:107]
	v_mfma_f32_16x16x32_bf16 v[92:95], v[178:181], v[220:223], v[92:95]
	v_mfma_f32_16x16x32_bf16 v[88:91], v[186:189], v[220:223], v[88:91]
	v_mfma_f32_16x16x32_bf16 v[76:79], v[178:181], v[228:231], v[76:79]
	v_mfma_f32_16x16x32_bf16 v[72:75], v[186:189], v[228:231], v[72:75]
	v_mfma_f32_16x16x32_bf16 v[68:71], v[178:181], v[236:239], v[68:71]
	v_mfma_f32_16x16x32_bf16 v[64:67], v[186:189], v[236:239], v[64:67]
	v_mfma_f32_16x16x32_bf16 v[108:111], v[182:185], v[216:219], v[108:111]
	v_mfma_f32_16x16x32_bf16 v[104:107], v[208:211], v[216:219], v[104:107]
	v_mfma_f32_16x16x32_bf16 v[92:95], v[182:185], v[224:227], v[92:95]
	v_mfma_f32_16x16x32_bf16 v[88:91], v[208:211], v[224:227], v[88:91]
	v_mfma_f32_16x16x32_bf16 v[76:79], v[182:185], v[232:235], v[76:79]
	v_mfma_f32_16x16x32_bf16 v[72:75], v[208:211], v[232:235], v[72:75]
	v_mfma_f32_16x16x32_bf16 v[68:71], v[182:185], v[240:243], v[68:71]
	v_mfma_f32_16x16x32_bf16 v[64:67], v[208:211], v[240:243], v[64:67]
	s_setprio 0
	s_barrier
	s_add_i32 s37, s37, s52
	v_lshl_add_u64 v[158:159], v[158:159], 0, s[26:27]
	s_mov_b32 m0, s37
	ds_read_b128 v[212:215], v168 offset:49152
	ds_read_b128 v[216:219], v168 offset:50176
	ds_read_b128 v[220:223], v168 offset:51200
	ds_read_b128 v[224:227], v168 offset:52224
	ds_read_b128 v[228:231], v168 offset:53248
	ds_read_b128 v[232:235], v168 offset:54272
	ds_read_b128 v[236:239], v168 offset:55296
	ds_read_b128 v[240:243], v168 offset:56320
	global_load_lds_dwordx4 v[158:159], off
	s_add_i32 m0, s37, 0x2000
	s_add_u32 s44, s44, 0x10080
	v_lshl_add_u64 v[158:159], v[174:175], 0, s[26:27]
	s_addc_u32 s45, s45, 0
	s_add_i32 s37, s39, s52
	global_load_lds_dwordx4 v[158:159], off
	v_lshl_add_u64 v[158:159], s[44:45], 0, v[132:133]
	s_mov_b32 m0, s37
	s_nop 0
	global_load_lds_dwordx4 v[158:159], off
	v_lshl_add_u64 v[158:159], s[44:45], 0, v[128:129]
	s_add_i32 m0, s37, 0x2000
	s_nop 0
	global_load_lds_dwordx4 v[158:159], off
	v_lshl_add_u64 v[158:159], v[244:245], 0, s[26:27]
	s_mov_b32 m0, s34
	s_nop 0
	global_load_lds_dwordx4 v[158:159], off
	v_lshl_add_u64 v[158:159], v[246:247], 0, s[26:27]
	s_mov_b32 m0, s53
	s_nop 0
	global_load_lds_dwordx4 v[158:159], off
	s_waitcnt vmcnt(8)
	s_waitcnt lgkmcnt(0)
	s_barrier
	s_setprio 1
	s_waitcnt lgkmcnt(0)
	v_mfma_f32_16x16x32_bf16 v[60:63], v[146:149], v[212:215], v[60:63]
	v_mfma_f32_16x16x32_bf16 v[56:59], v[154:157], v[212:215], v[56:59]
	v_mfma_f32_16x16x32_bf16 v[52:55], v[146:149], v[220:223], v[52:55]
	v_mfma_f32_16x16x32_bf16 v[48:51], v[154:157], v[220:223], v[48:51]
	v_mfma_f32_16x16x32_bf16 v[36:39], v[146:149], v[228:231], v[36:39]
	v_mfma_f32_16x16x32_bf16 v[32:35], v[154:157], v[228:231], v[32:35]
	v_mfma_f32_16x16x32_bf16 v[20:23], v[146:149], v[236:239], v[20:23]
	v_mfma_f32_16x16x32_bf16 v[16:19], v[154:157], v[236:239], v[16:19]
	v_mfma_f32_16x16x32_bf16 v[60:63], v[150:153], v[216:219], v[60:63]
	v_mfma_f32_16x16x32_bf16 v[56:59], v[170:173], v[216:219], v[56:59]
	v_mfma_f32_16x16x32_bf16 v[52:55], v[150:153], v[224:227], v[52:55]
	v_mfma_f32_16x16x32_bf16 v[48:51], v[170:173], v[224:227], v[48:51]
	v_mfma_f32_16x16x32_bf16 v[36:39], v[150:153], v[232:235], v[36:39]
	v_mfma_f32_16x16x32_bf16 v[32:35], v[170:173], v[232:235], v[32:35]
	v_mfma_f32_16x16x32_bf16 v[20:23], v[150:153], v[240:243], v[20:23]
	v_mfma_f32_16x16x32_bf16 v[16:19], v[170:173], v[240:243], v[16:19]
	s_setprio 0
	s_setprio 1
	v_mfma_f32_16x16x32_bf16 v[44:47], v[178:181], v[212:215], v[44:47]
	v_mfma_f32_16x16x32_bf16 v[40:43], v[186:189], v[212:215], v[40:43]
	v_mfma_f32_16x16x32_bf16 v[28:31], v[178:181], v[220:223], v[28:31]
	v_mfma_f32_16x16x32_bf16 v[24:27], v[186:189], v[220:223], v[24:27]
	v_mfma_f32_16x16x32_bf16 v[12:15], v[178:181], v[228:231], v[12:15]
	v_mfma_f32_16x16x32_bf16 v[8:11], v[186:189], v[228:231], v[8:11]
	v_mfma_f32_16x16x32_bf16 v[4:7], v[178:181], v[236:239], v[4:7]
	v_mfma_f32_16x16x32_bf16 v[0:3], v[186:189], v[236:239], v[0:3]
	v_mfma_f32_16x16x32_bf16 v[44:47], v[182:185], v[216:219], v[44:47]
	v_mfma_f32_16x16x32_bf16 v[40:43], v[208:211], v[216:219], v[40:43]
	v_mfma_f32_16x16x32_bf16 v[28:31], v[182:185], v[224:227], v[28:31]
	v_mfma_f32_16x16x32_bf16 v[24:27], v[208:211], v[224:227], v[24:27]
	v_mfma_f32_16x16x32_bf16 v[12:15], v[182:185], v[232:235], v[12:15]
	v_mfma_f32_16x16x32_bf16 v[8:11], v[208:211], v[232:235], v[8:11]
	v_mfma_f32_16x16x32_bf16 v[4:7], v[182:185], v[240:243], v[4:7]
	v_mfma_f32_16x16x32_bf16 v[0:3], v[208:211], v[240:243], v[0:3]
	s_setprio 0
	s_barrier
	s_add_i32 s64, s64, 2
	s_add_u32 s42, s42, 0x100
	s_addc_u32 s43, s43, 0
	s_add_u32 s22, s22, 0x100
	s_addc_u32 s30, s30, 0
	s_cmp_gt_u32 s64, 13
	s_cbranch_scc0 .LBB0_645
	v_readlane_b32 s0, v252, 26
	v_readlane_b32 s1, v252, 27
	s_and_b64 vcc, exec, s[0:1]
	v_readlane_b32 s68, v252, 11
	v_readlane_b32 s69, v252, 12
	s_cbranch_vccz .LBB0_648
	s_barrier

.Lrwd_ip21:
	s_waitcnt lgkmcnt(0)
	s_barrier
	s_setprio 1
	s_waitcnt lgkmcnt(0)
	v_mfma_f32_16x16x32_bf16 v[60:63], v[146:149], v[212:215], v[60:63]
	v_mfma_f32_16x16x32_bf16 v[56:59], v[154:157], v[212:215], v[56:59]
	v_mfma_f32_16x16x32_bf16 v[52:55], v[146:149], v[220:223], v[52:55]
	v_mfma_f32_16x16x32_bf16 v[48:51], v[154:157], v[220:223], v[48:51]
	v_mfma_f32_16x16x32_bf16 v[36:39], v[146:149], v[228:231], v[36:39]
	v_mfma_f32_16x16x32_bf16 v[32:35], v[154:157], v[228:231], v[32:35]
	v_mfma_f32_16x16x32_bf16 v[20:23], v[146:149], v[236:239], v[20:23]
	v_mfma_f32_16x16x32_bf16 v[16:19], v[154:157], v[236:239], v[16:19]
	v_mfma_f32_16x16x32_bf16 v[60:63], v[150:153], v[216:219], v[60:63]
	v_mfma_f32_16x16x32_bf16 v[56:59], v[170:173], v[216:219], v[56:59]
	v_mfma_f32_16x16x32_bf16 v[52:55], v[150:153], v[224:227], v[52:55]
	v_mfma_f32_16x16x32_bf16 v[48:51], v[170:173], v[224:227], v[48:51]
	v_mfma_f32_16x16x32_bf16 v[36:39], v[150:153], v[232:235], v[36:39]
	v_mfma_f32_16x16x32_bf16 v[32:35], v[170:173], v[232:235], v[32:35]
	v_mfma_f32_16x16x32_bf16 v[20:23], v[150:153], v[240:243], v[20:23]
	v_mfma_f32_16x16x32_bf16 v[16:19], v[170:173], v[240:243], v[16:19]
	s_setprio 0
	s_setprio 1
	v_mfma_f32_16x16x32_bf16 v[44:47], v[178:181], v[212:215], v[44:47]
	v_mfma_f32_16x16x32_bf16 v[40:43], v[186:189], v[212:215], v[40:43]
	v_mfma_f32_16x16x32_bf16 v[28:31], v[178:181], v[220:223], v[28:31]
	v_mfma_f32_16x16x32_bf16 v[24:27], v[186:189], v[220:223], v[24:27]
	v_mfma_f32_16x16x32_bf16 v[12:15], v[178:181], v[228:231], v[12:15]
	v_mfma_f32_16x16x32_bf16 v[8:11], v[186:189], v[228:231], v[8:11]
	v_mfma_f32_16x16x32_bf16 v[4:7], v[178:181], v[236:239], v[4:7]
	v_mfma_f32_16x16x32_bf16 v[0:3], v[186:189], v[236:239], v[0:3]
	v_mfma_f32_16x16x32_bf16 v[44:47], v[182:185], v[216:219], v[44:47]
	v_mfma_f32_16x16x32_bf16 v[40:43], v[208:211], v[216:219], v[40:43]
	v_mfma_f32_16x16x32_bf16 v[28:31], v[182:185], v[224:227], v[28:31]
	v_mfma_f32_16x16x32_bf16 v[24:27], v[208:211], v[224:227], v[24:27]
	v_mfma_f32_16x16x32_bf16 v[12:15], v[182:185], v[232:235], v[12:15]
	v_mfma_f32_16x16x32_bf16 v[8:11], v[208:211], v[232:235], v[8:11]
	v_mfma_f32_16x16x32_bf16 v[4:7], v[182:185], v[240:243], v[4:7]
	v_mfma_f32_16x16x32_bf16 v[0:3], v[208:211], v[240:243], v[0:3]
	s_setprio 0
	s_barrier
	s_add_i32 s37, 0, 0x18000
	v_add_u32_e32 v145, s37, v162
	s_add_i32 s39, 0, 0x1c000
	ds_read_b128 v[146:149], v145
	ds_read_b128 v[150:153], v145 offset:1024
	ds_read_b128 v[154:157], v145 offset:2048
	ds_read_b128 v[170:173], v145 offset:3072
	v_add_u32_e32 v145, s39, v162
	ds_read_b128 v[178:181], v145
	ds_read_b128 v[182:185], v145 offset:1024
	ds_read_b128 v[186:189], v145 offset:2048
	ds_read_b128 v[208:211], v145 offset:3072
	s_add_u32 s62, s62, 0x40000
	s_addc_u32 s63, s63, 0
	s_mov_b32 m0, s54
	v_lshl_add_u64 v[248:249], s[62:63], 0, v[134:135]
	ds_read_b128 v[212:215], v168 offset:32768
	ds_read_b128 v[216:219], v168 offset:33792
	ds_read_b128 v[220:223], v168 offset:34816
	ds_read_b128 v[224:227], v168 offset:35840
	ds_read_b128 v[228:231], v168 offset:36864
	ds_read_b128 v[232:235], v168 offset:37888
	ds_read_b128 v[236:239], v168 offset:38912
	ds_read_b128 v[240:243], v168 offset:39936
	global_load_lds_dwordx4 v[248:249], off
	v_lshl_add_u64 v[248:249], s[62:63], 0, v[130:131]
	s_mov_b32 m0, s55
	s_nop 0
	global_load_lds_dwordx4 v[248:249], off
	s_cmp_eq_u32 s64, -2
	s_cbranch_scc0 .Lrw8_ip22
	s_cmp_gt_u32 s34, 1
	s_cbranch_scc0 .Lrw8_ip22
	s_waitcnt vmcnt(26)
	s_branch .Lrwd_ip22

.Lrwd_ip22:
	s_waitcnt lgkmcnt(0)
	s_barrier
	s_setprio 1
	s_waitcnt lgkmcnt(0)
	v_mfma_f32_16x16x32_bf16 v[124:127], v[146:149], v[212:215], v[124:127]
	v_mfma_f32_16x16x32_bf16 v[120:123], v[154:157], v[212:215], v[120:123]
	v_mfma_f32_16x16x32_bf16 v[116:119], v[146:149], v[220:223], v[116:119]
	v_mfma_f32_16x16x32_bf16 v[112:115], v[154:157], v[220:223], v[112:115]
	v_mfma_f32_16x16x32_bf16 v[100:103], v[146:149], v[228:231], v[100:103]
	v_mfma_f32_16x16x32_bf16 v[96:99], v[154:157], v[228:231], v[96:99]
	v_mfma_f32_16x16x32_bf16 v[84:87], v[146:149], v[236:239], v[84:87]
	v_mfma_f32_16x16x32_bf16 v[80:83], v[154:157], v[236:239], v[80:83]
	v_mfma_f32_16x16x32_bf16 v[124:127], v[150:153], v[216:219], v[124:127]
	v_mfma_f32_16x16x32_bf16 v[120:123], v[170:173], v[216:219], v[120:123]
	v_mfma_f32_16x16x32_bf16 v[116:119], v[150:153], v[224:227], v[116:119]
	v_mfma_f32_16x16x32_bf16 v[112:115], v[170:173], v[224:227], v[112:115]
	v_mfma_f32_16x16x32_bf16 v[100:103], v[150:153], v[232:235], v[100:103]
	v_mfma_f32_16x16x32_bf16 v[96:99], v[170:173], v[232:235], v[96:99]
	v_mfma_f32_16x16x32_bf16 v[84:87], v[150:153], v[240:243], v[84:87]
	v_mfma_f32_16x16x32_bf16 v[80:83], v[170:173], v[240:243], v[80:83]
	s_setprio 0
	s_setprio 1
	v_mfma_f32_16x16x32_bf16 v[108:111], v[178:181], v[212:215], v[108:111]
	v_mfma_f32_16x16x32_bf16 v[104:107], v[186:189], v[212:215], v[104:107]
	v_mfma_f32_16x16x32_bf16 v[92:95], v[178:181], v[220:223], v[92:95]
	v_mfma_f32_16x16x32_bf16 v[88:91], v[186:189], v[220:223], v[88:91]
	v_mfma_f32_16x16x32_bf16 v[76:79], v[178:181], v[228:231], v[76:79]
	v_mfma_f32_16x16x32_bf16 v[72:75], v[186:189], v[228:231], v[72:75]
	v_mfma_f32_16x16x32_bf16 v[68:71], v[178:181], v[236:239], v[68:71]
	v_mfma_f32_16x16x32_bf16 v[64:67], v[186:189], v[236:239], v[64:67]
	v_mfma_f32_16x16x32_bf16 v[108:111], v[182:185], v[216:219], v[108:111]
	v_mfma_f32_16x16x32_bf16 v[104:107], v[208:211], v[216:219], v[104:107]
	v_mfma_f32_16x16x32_bf16 v[92:95], v[182:185], v[224:227], v[92:95]
	v_mfma_f32_16x16x32_bf16 v[88:91], v[208:211], v[224:227], v[88:91]
	v_mfma_f32_16x16x32_bf16 v[76:79], v[182:185], v[232:235], v[76:79]
	v_mfma_f32_16x16x32_bf16 v[72:75], v[208:211], v[232:235], v[72:75]
	v_mfma_f32_16x16x32_bf16 v[68:71], v[182:185], v[240:243], v[68:71]
	v_mfma_f32_16x16x32_bf16 v[64:67], v[208:211], v[240:243], v[64:67]
	s_setprio 0
	s_barrier
	s_add_i32 s37, s37, s52
	v_lshl_add_u64 v[158:159], v[158:159], 0, s[26:27]
	s_mov_b32 m0, s37
	ds_read_b128 v[212:215], v168 offset:49152
	ds_read_b128 v[216:219], v168 offset:50176
	ds_read_b128 v[220:223], v168 offset:51200
	ds_read_b128 v[224:227], v168 offset:52224
	ds_read_b128 v[228:231], v168 offset:53248
	ds_read_b128 v[232:235], v168 offset:54272
	ds_read_b128 v[236:239], v168 offset:55296
	ds_read_b128 v[240:243], v168 offset:56320
	global_load_lds_dwordx4 v[158:159], off
	s_add_i32 m0, s37, 0x2000
	s_add_u32 s44, s44, 0x10080
	v_lshl_add_u64 v[158:159], v[174:175], 0, s[26:27]
	s_addc_u32 s45, s45, 0
	s_add_i32 s37, s39, s52
	global_load_lds_dwordx4 v[158:159], off
	v_lshl_add_u64 v[158:159], s[44:45], 0, v[132:133]
	s_mov_b32 m0, s37
	s_nop 0
	global_load_lds_dwordx4 v[158:159], off
	v_lshl_add_u64 v[158:159], s[44:45], 0, v[128:129]
	s_add_i32 m0, s37, 0x2000
	s_nop 0
	global_load_lds_dwordx4 v[158:159], off
	v_lshl_add_u64 v[158:159], v[244:245], 0, s[26:27]
	s_mov_b32 m0, s35
	s_nop 0
	global_load_lds_dwordx4 v[158:159], off
	v_lshl_add_u64 v[158:159], v[246:247], 0, s[26:27]
	s_mov_b32 m0, s53
	s_nop 0
	global_load_lds_dwordx4 v[158:159], off
	s_waitcnt vmcnt(8)
	s_waitcnt lgkmcnt(0)
	s_barrier
	s_setprio 1
	s_waitcnt lgkmcnt(0)
	v_mfma_f32_16x16x32_bf16 v[60:63], v[146:149], v[212:215], v[60:63]
	v_mfma_f32_16x16x32_bf16 v[56:59], v[154:157], v[212:215], v[56:59]
	v_mfma_f32_16x16x32_bf16 v[52:55], v[146:149], v[220:223], v[52:55]
	v_mfma_f32_16x16x32_bf16 v[48:51], v[154:157], v[220:223], v[48:51]
	v_mfma_f32_16x16x32_bf16 v[36:39], v[146:149], v[228:231], v[36:39]
	v_mfma_f32_16x16x32_bf16 v[32:35], v[154:157], v[228:231], v[32:35]
	v_mfma_f32_16x16x32_bf16 v[20:23], v[146:149], v[236:239], v[20:23]
	v_mfma_f32_16x16x32_bf16 v[16:19], v[154:157], v[236:239], v[16:19]
	v_mfma_f32_16x16x32_bf16 v[60:63], v[150:153], v[216:219], v[60:63]
	v_mfma_f32_16x16x32_bf16 v[56:59], v[170:173], v[216:219], v[56:59]
	v_mfma_f32_16x16x32_bf16 v[52:55], v[150:153], v[224:227], v[52:55]
	v_mfma_f32_16x16x32_bf16 v[48:51], v[170:173], v[224:227], v[48:51]
	v_mfma_f32_16x16x32_bf16 v[36:39], v[150:153], v[232:235], v[36:39]
	v_mfma_f32_16x16x32_bf16 v[32:35], v[170:173], v[232:235], v[32:35]
	v_mfma_f32_16x16x32_bf16 v[20:23], v[150:153], v[240:243], v[20:23]
	v_mfma_f32_16x16x32_bf16 v[16:19], v[170:173], v[240:243], v[16:19]
	s_setprio 0
	s_setprio 1
	v_mfma_f32_16x16x32_bf16 v[44:47], v[178:181], v[212:215], v[44:47]
	v_mfma_f32_16x16x32_bf16 v[40:43], v[186:189], v[212:215], v[40:43]
	v_mfma_f32_16x16x32_bf16 v[28:31], v[178:181], v[220:223], v[28:31]
	v_mfma_f32_16x16x32_bf16 v[24:27], v[186:189], v[220:223], v[24:27]
	v_mfma_f32_16x16x32_bf16 v[12:15], v[178:181], v[228:231], v[12:15]
	v_mfma_f32_16x16x32_bf16 v[8:11], v[186:189], v[228:231], v[8:11]
	v_mfma_f32_16x16x32_bf16 v[4:7], v[178:181], v[236:239], v[4:7]
	v_mfma_f32_16x16x32_bf16 v[0:3], v[186:189], v[236:239], v[0:3]
	v_mfma_f32_16x16x32_bf16 v[44:47], v[182:185], v[216:219], v[44:47]
	v_mfma_f32_16x16x32_bf16 v[40:43], v[208:211], v[216:219], v[40:43]
	v_mfma_f32_16x16x32_bf16 v[28:31], v[182:185], v[224:227], v[28:31]
	v_mfma_f32_16x16x32_bf16 v[24:27], v[208:211], v[224:227], v[24:27]
	v_mfma_f32_16x16x32_bf16 v[12:15], v[182:185], v[232:235], v[12:15]
	v_mfma_f32_16x16x32_bf16 v[8:11], v[208:211], v[232:235], v[8:11]
	v_mfma_f32_16x16x32_bf16 v[4:7], v[182:185], v[240:243], v[4:7]
	v_mfma_f32_16x16x32_bf16 v[0:3], v[208:211], v[240:243], v[0:3]
	s_setprio 0
	s_barrier
	s_add_i32 s64, s64, 2
	s_add_u32 s42, s42, 0x100
	s_addc_u32 s43, s43, 0
	s_add_u32 s22, s22, 0x100
	s_addc_u32 s30, s30, 0
	s_cmp_gt_u32 s64, 13
	s_cbranch_scc0 .LBB0_1180
	v_readlane_b32 s0, v252, 26
	v_readlane_b32 s1, v252, 27
	s_and_b64 vcc, exec, s[0:1]
	v_readlane_b32 s68, v252, 11
	v_readlane_b32 s69, v252, 12
	s_cbranch_vccz .LBB0_1183
	s_barrier
